# attention softmax segment: four pad nops per tile removed where the packed sums already separate each exp from its reader
# speedup vs baseline: 1.0065x; 1.0065x over previous
.Lat2_back_8:
	v_exp_f32_e32 v64, v64
	v_exp_f32_e32 v65, v65
	v_exp_f32_e32 v66, v66
	v_exp_f32_e32 v67, v67
	v_exp_f32_e32 v68, v68
	v_exp_f32_e32 v69, v69
	v_exp_f32_e32 v70, v70
	v_exp_f32_e32 v71, v71
	v_pk_add_f32 v[232:233], v[232:233], v[64:65]
	v_pk_add_f32 v[234:235], v[234:235], v[66:67]
	v_pk_add_f32 v[232:233], v[232:233], v[68:69]
	v_pk_add_f32 v[234:235], v[234:235], v[70:71]
	v_cvt_pk_bf16_f32 v64, v64, v65
	v_cvt_pk_bf16_f32 v65, v66, v67
	v_cvt_pk_bf16_f32 v66, v68, v69
	v_cvt_pk_bf16_f32 v67, v70, v71
	s_waitcnt lgkmcnt(0)
	s_nop 0
	v_mfma_f32_32x32x16_bf16 v[0:15], v[64:67], v[164:167], v[0:15]
	v_exp_f32_e32 v72, v72
	v_exp_f32_e32 v73, v73
	v_mfma_f32_32x32x16_bf16 v[16:31], v[64:67], v[168:171], v[16:31]
	ds_read_b64_tr_b16 v[164:165], v206 offset:2048
	ds_read_b64_tr_b16 v[166:167], v206 offset:2560
	v_exp_f32_e32 v74, v74
	v_exp_f32_e32 v75, v75
	v_pk_add_f32 v[232:233], v[232:233], v[72:73]
	v_mfma_f32_32x32x16_bf16 v[32:47], v[64:67], v[172:175], v[32:47]
	ds_read_b64_tr_b16 v[168:169], v206 offset:6144
	ds_read_b64_tr_b16 v[170:171], v206 offset:6656
	v_exp_f32_e32 v76, v76
	v_exp_f32_e32 v77, v77
	v_pk_add_f32 v[234:235], v[234:235], v[74:75]
	v_mfma_f32_32x32x16_bf16 v[48:63], v[64:67], v[176:179], v[48:63]
	ds_read_b64_tr_b16 v[172:173], v206 offset:10240
	ds_read_b64_tr_b16 v[174:175], v206 offset:10752
	v_exp_f32_e32 v78, v78
	v_exp_f32_e32 v79, v79
	v_pk_add_f32 v[232:233], v[232:233], v[76:77]
	v_pk_add_f32 v[234:235], v[234:235], v[78:79]
	v_cvt_pk_bf16_f32 v72, v72, v73
	v_cvt_pk_bf16_f32 v73, v74, v75
	v_cvt_pk_bf16_f32 v74, v76, v77
	v_cvt_pk_bf16_f32 v75, v78, v79
	s_nop 1
	v_mfma_f32_32x32x16_bf16 v[0:15], v[72:75], v[180:183], v[0:15]
	ds_read_b64_tr_b16 v[176:177], v206 offset:14336
	ds_read_b64_tr_b16 v[178:179], v206 offset:14848
	v_exp_f32_e32 v80, v80
	v_exp_f32_e32 v81, v81
	v_mfma_f32_32x32x16_bf16 v[16:31], v[72:75], v[184:187], v[16:31]
	ds_read_b64_tr_b16 v[180:181], v206 offset:3072
	ds_read_b64_tr_b16 v[182:183], v206 offset:3584
	v_exp_f32_e32 v82, v82
	v_exp_f32_e32 v83, v83
	v_pk_add_f32 v[232:233], v[232:233], v[80:81]
	v_mfma_f32_32x32x16_bf16 v[32:47], v[72:75], v[188:191], v[32:47]
	ds_read_b64_tr_b16 v[184:185], v206 offset:7168
	ds_read_b64_tr_b16 v[186:187], v206 offset:7680
	v_exp_f32_e32 v84, v84
	v_exp_f32_e32 v85, v85
	v_pk_add_f32 v[234:235], v[234:235], v[82:83]
	v_mfma_f32_32x32x16_bf16 v[48:63], v[72:75], v[192:195], v[48:63]
	ds_read_b64_tr_b16 v[188:189], v206 offset:11264
	ds_read_b64_tr_b16 v[190:191], v206 offset:11776
	v_exp_f32_e32 v86, v86
	v_exp_f32_e32 v87, v87
	v_pk_add_f32 v[232:233], v[232:233], v[84:85]
	v_pk_add_f32 v[234:235], v[234:235], v[86:87]
	v_cvt_pk_bf16_f32 v80, v80, v81
	v_cvt_pk_bf16_f32 v81, v82, v83
	v_cvt_pk_bf16_f32 v82, v84, v85
	v_cvt_pk_bf16_f32 v83, v86, v87
	s_nop 1
	s_waitcnt lgkmcnt(12)
	v_mfma_f32_32x32x16_bf16 v[0:15], v[80:83], v[164:167], v[0:15]
	ds_read_b64_tr_b16 v[192:193], v206 offset:15360
	ds_read_b64_tr_b16 v[194:195], v206 offset:15872
	v_exp_f32_e32 v88, v88
	v_exp_f32_e32 v89, v89
	s_waitcnt lgkmcnt(12)
	v_mfma_f32_32x32x16_bf16 v[16:31], v[80:83], v[168:171], v[16:31]
	v_exp_f32_e32 v90, v90
	v_exp_f32_e32 v91, v91
	v_pk_add_f32 v[232:233], v[232:233], v[88:89]
	s_waitcnt lgkmcnt(10)
	v_mfma_f32_32x32x16_bf16 v[32:47], v[80:83], v[172:175], v[32:47]
	v_exp_f32_e32 v92, v92
	v_exp_f32_e32 v93, v93
	v_pk_add_f32 v[234:235], v[234:235], v[90:91]
	s_waitcnt lgkmcnt(8)
	v_mfma_f32_32x32x16_bf16 v[48:63], v[80:83], v[176:179], v[48:63]
	v_exp_f32_e32 v94, v94
	v_exp_f32_e32 v95, v95
	v_pk_add_f32 v[232:233], v[232:233], v[92:93]
	v_pk_add_f32 v[234:235], v[234:235], v[94:95]
	v_cvt_pk_bf16_f32 v88, v88, v89
	v_cvt_pk_bf16_f32 v89, v90, v91
	v_cvt_pk_bf16_f32 v90, v92, v93
	v_cvt_pk_bf16_f32 v91, v94, v95
	s_nop 1
	s_waitcnt lgkmcnt(6)
	v_mfma_f32_32x32x16_bf16 v[0:15], v[88:91], v[180:183], v[0:15]
	s_waitcnt lgkmcnt(4)
	v_mfma_f32_32x32x16_bf16 v[16:31], v[88:91], v[184:187], v[16:31]
	s_waitcnt lgkmcnt(2)
	v_mfma_f32_32x32x16_bf16 v[32:47], v[88:91], v[188:191], v[32:47]
	s_waitcnt lgkmcnt(0)
	v_mfma_f32_32x32x16_bf16 v[48:63], v[88:91], v[192:195], v[48:63]
	s_mov_b32 s4, s59
	s_mov_b32 s59, s60
	s_mov_b32 s60, s61
	s_mov_b32 s61, s25
	s_mov_b32 s25, s4
	s_add_i32 s45, s45, 1
	s_mov_b32 s62, 0x41000000
	s_mov_b32 s47, 0
	s_nop 0
	s_waitcnt vmcnt(6)

.Lat2_back_18:
	v_exp_f32_e32 v64, v64
	v_exp_f32_e32 v65, v65
	v_exp_f32_e32 v66, v66
	v_exp_f32_e32 v67, v67
	v_exp_f32_e32 v68, v68
	v_exp_f32_e32 v69, v69
	v_exp_f32_e32 v70, v70
	v_exp_f32_e32 v71, v71
	v_pk_add_f32 v[232:233], v[232:233], v[64:65]
	v_pk_add_f32 v[234:235], v[234:235], v[66:67]
	v_pk_add_f32 v[232:233], v[232:233], v[68:69]
	v_pk_add_f32 v[234:235], v[234:235], v[70:71]
	v_cvt_pk_bf16_f32 v64, v64, v65
	v_cvt_pk_bf16_f32 v65, v66, v67
	v_cvt_pk_bf16_f32 v66, v68, v69
	v_cvt_pk_bf16_f32 v67, v70, v71
	s_waitcnt lgkmcnt(0)
	s_nop 0
	v_mfma_f32_32x32x16_bf16 v[0:15], v[64:67], v[164:167], v[0:15]
	v_exp_f32_e32 v72, v72
	v_exp_f32_e32 v73, v73
	v_mfma_f32_32x32x16_bf16 v[16:31], v[64:67], v[168:171], v[16:31]
	ds_read_b64_tr_b16 v[164:165], v206 offset:2048
	ds_read_b64_tr_b16 v[166:167], v206 offset:2560
	v_exp_f32_e32 v74, v74
	v_exp_f32_e32 v75, v75
	v_pk_add_f32 v[232:233], v[232:233], v[72:73]
	v_mfma_f32_32x32x16_bf16 v[32:47], v[64:67], v[172:175], v[32:47]
	ds_read_b64_tr_b16 v[168:169], v206 offset:6144
	ds_read_b64_tr_b16 v[170:171], v206 offset:6656
	v_exp_f32_e32 v76, v76
	v_exp_f32_e32 v77, v77
	v_pk_add_f32 v[234:235], v[234:235], v[74:75]
	v_mfma_f32_32x32x16_bf16 v[48:63], v[64:67], v[176:179], v[48:63]
	ds_read_b64_tr_b16 v[172:173], v206 offset:10240
	ds_read_b64_tr_b16 v[174:175], v206 offset:10752
	v_exp_f32_e32 v78, v78
	v_exp_f32_e32 v79, v79
	v_pk_add_f32 v[232:233], v[232:233], v[76:77]
	v_pk_add_f32 v[234:235], v[234:235], v[78:79]
	v_cvt_pk_bf16_f32 v72, v72, v73
	v_cvt_pk_bf16_f32 v73, v74, v75
	v_cvt_pk_bf16_f32 v74, v76, v77
	v_cvt_pk_bf16_f32 v75, v78, v79
	s_nop 1
	v_mfma_f32_32x32x16_bf16 v[0:15], v[72:75], v[180:183], v[0:15]
	ds_read_b64_tr_b16 v[176:177], v206 offset:14336
	ds_read_b64_tr_b16 v[178:179], v206 offset:14848
	v_exp_f32_e32 v80, v80
	v_exp_f32_e32 v81, v81
	v_mfma_f32_32x32x16_bf16 v[16:31], v[72:75], v[184:187], v[16:31]
	ds_read_b64_tr_b16 v[180:181], v206 offset:3072
	ds_read_b64_tr_b16 v[182:183], v206 offset:3584
	v_exp_f32_e32 v82, v82
	v_exp_f32_e32 v83, v83
	v_pk_add_f32 v[232:233], v[232:233], v[80:81]
	v_mfma_f32_32x32x16_bf16 v[32:47], v[72:75], v[188:191], v[32:47]
	ds_read_b64_tr_b16 v[184:185], v206 offset:7168
	ds_read_b64_tr_b16 v[186:187], v206 offset:7680
	v_exp_f32_e32 v84, v84
	v_exp_f32_e32 v85, v85
	v_pk_add_f32 v[234:235], v[234:235], v[82:83]
	v_mfma_f32_32x32x16_bf16 v[48:63], v[72:75], v[192:195], v[48:63]
	ds_read_b64_tr_b16 v[188:189], v206 offset:11264
	ds_read_b64_tr_b16 v[190:191], v206 offset:11776
	v_exp_f32_e32 v86, v86
	v_exp_f32_e32 v87, v87
	v_pk_add_f32 v[232:233], v[232:233], v[84:85]
	v_pk_add_f32 v[234:235], v[234:235], v[86:87]
	v_cvt_pk_bf16_f32 v80, v80, v81
	v_cvt_pk_bf16_f32 v81, v82, v83
	v_cvt_pk_bf16_f32 v82, v84, v85
	v_cvt_pk_bf16_f32 v83, v86, v87
	s_nop 1
	s_waitcnt lgkmcnt(12)
	v_mfma_f32_32x32x16_bf16 v[0:15], v[80:83], v[164:167], v[0:15]
	ds_read_b64_tr_b16 v[192:193], v206 offset:15360
	ds_read_b64_tr_b16 v[194:195], v206 offset:15872
	v_exp_f32_e32 v88, v88
	v_exp_f32_e32 v89, v89
	s_waitcnt lgkmcnt(12)
	v_mfma_f32_32x32x16_bf16 v[16:31], v[80:83], v[168:171], v[16:31]
	v_exp_f32_e32 v90, v90
	v_exp_f32_e32 v91, v91
	v_pk_add_f32 v[232:233], v[232:233], v[88:89]
	s_waitcnt lgkmcnt(10)
	v_mfma_f32_32x32x16_bf16 v[32:47], v[80:83], v[172:175], v[32:47]
	v_exp_f32_e32 v92, v92
	v_exp_f32_e32 v93, v93
	v_pk_add_f32 v[234:235], v[234:235], v[90:91]
	s_waitcnt lgkmcnt(8)
	v_mfma_f32_32x32x16_bf16 v[48:63], v[80:83], v[176:179], v[48:63]
	v_exp_f32_e32 v94, v94
	v_exp_f32_e32 v95, v95
	v_pk_add_f32 v[232:233], v[232:233], v[92:93]
	v_pk_add_f32 v[234:235], v[234:235], v[94:95]
	v_cvt_pk_bf16_f32 v88, v88, v89
	v_cvt_pk_bf16_f32 v89, v90, v91
	v_cvt_pk_bf16_f32 v90, v92, v93
	v_cvt_pk_bf16_f32 v91, v94, v95
	s_nop 1
	s_waitcnt lgkmcnt(6)
	v_mfma_f32_32x32x16_bf16 v[0:15], v[88:91], v[180:183], v[0:15]
	s_waitcnt lgkmcnt(4)
	v_mfma_f32_32x32x16_bf16 v[16:31], v[88:91], v[184:187], v[16:31]
	s_waitcnt lgkmcnt(2)
	v_mfma_f32_32x32x16_bf16 v[32:47], v[88:91], v[188:191], v[32:47]
	s_waitcnt lgkmcnt(0)
	v_mfma_f32_32x32x16_bf16 v[48:63], v[88:91], v[192:195], v[48:63]
